# grid barrier: early L2 write-back hint issued by the workgroup arriving 4 before the XCD-last
# speedup vs baseline: 1.0097x; 1.0045x over previous
; __device__ __forceinline__ unsigned xb_add(unsigned* p, unsigned v) { return __hip_atomic_fetch_add(p, v, __ATOMIC_RELAXED, __HIP_MEMORY_SCOPE_AGENT); }
; __device__ __forceinline__ void xcd_barrier(const XcdBarrier& b) {
;     ...
;         const unsigned old = xb_add(&bar[XB_XSUB(b.x)], 1u);
;         const unsigned gen = old / nloc;
;         if (old + 1u == (gen + 1u) * nloc) {
;             __builtin_amdgcn_fence(__ATOMIC_RELEASE, "agent");
;             asm volatile("s_waitcnt vmcnt(0)" ::: "memory");
;             const unsigned og = xb_add(&bar[XB_TOP], 1u);
.Lxb0_hint:
	v_add_u32_e32 v8, 4, v6
	v_cmp_eq_u32_e32 vcc, v8, v4
	s_cbranch_vccz .Lxb0_early
	buffer_wbl2 sc1
